# attention loop: wave-half priorities alternate every 6 MFMA groups (4 toggles per iteration, immediates in the per-half copies) instead of every 12
# speedup vs baseline: 1.0172x; 1.0172x over previous
.Lan_331_h0:
	v_cvt_f32_i32_e32 v237, v231
	s_setprio 1
	s_waitcnt lgkmcnt(4)
	v_mfma_f32_32x32x16_bf16 v[96:111], v[64:67], v[112:115], v[96:111]
	ds_read_b128 v[244:247], v234 offset:34848
	v_exp_f32_e32 v80, v80
	v_exp_f32_e32 v81, v81
	v_add_f32_e32 v238, 0, v80
	v_add_f32_e32 v238, v238, v81
	s_waitcnt lgkmcnt(4)
	v_mfma_f32_32x32x16_bf16 v[96:111], v[68:71], v[116:119], v[96:111]
	ds_read_b128 v[64:67], v234 offset:39424
	v_exp_f32_e32 v82, v82
	v_exp_f32_e32 v83, v83
	v_add_f32_e32 v238, v238, v82
	v_add_f32_e32 v238, v238, v83
	s_waitcnt lgkmcnt(4)
	v_mfma_f32_32x32x16_bf16 v[96:111], v[72:75], v[120:123], v[96:111]
	ds_read_b128 v[68:71], v234 offset:39456
	v_exp_f32_e32 v84, v84
	v_exp_f32_e32 v85, v85
	v_add_f32_e32 v238, v238, v84
	v_add_f32_e32 v238, v238, v85
	s_waitcnt lgkmcnt(4)
	v_mfma_f32_32x32x16_bf16 v[96:111], v[76:79], v[124:127], v[96:111]
	ds_read_b128 v[72:75], v234 offset:44032
	v_exp_f32_e32 v86, v86
	v_exp_f32_e32 v87, v87
	v_add_f32_e32 v238, v238, v86
	v_add_f32_e32 v238, v238, v87
	s_waitcnt lgkmcnt(4)
	v_mfma_f32_32x32x16_bf16 v[48:63], v[160:163], v[144:147], v[48:63]
	ds_read_b128 v[76:79], v234 offset:44064
	v_cvt_pk_bf16_f32 v152, v80, v81
	v_cvt_pk_bf16_f32 v153, v82, v83
	v_cvt_pk_bf16_f32 v154, v84, v85
	v_cvt_pk_bf16_f32 v155, v86, v87
	v_add_f32_e32 v255, 0x42800000, v237
	v_fma_f32 v254, v236, v255, v253
	s_waitcnt lgkmcnt(4)
	v_mfma_f32_32x32x16_bf16 v[48:63], v[244:247], v[148:151], v[48:63]
	ds_read_b128 v[160:163], v234 offset:48640
	v_exp_f32_e32 v88, v88
	v_exp_f32_e32 v89, v89
	v_add_f32_e32 v238, v238, v88
	v_add_f32_e32 v238, v238, v89
	v_fmamk_f32 v80, v201, 0x42000000, v254
	v_fmamk_f32 v81, v201, 0x42040000, v254
	s_setprio 0
	s_waitcnt lgkmcnt(4)
	v_mfma_f32_32x32x16_bf16 v[32:47], v[64:67], v[144:147], v[32:47]
	ds_read_b128 v[244:247], v234 offset:48672
	v_exp_f32_e32 v90, v90
	v_exp_f32_e32 v91, v91
	v_add_f32_e32 v238, v238, v90
	v_add_f32_e32 v238, v238, v91
	v_fmamk_f32 v82, v201, 0x42080000, v254
	v_fmamk_f32 v83, v201, 0x420c0000, v254
	s_waitcnt lgkmcnt(4)
	v_mfma_f32_32x32x16_bf16 v[32:47], v[68:71], v[148:151], v[32:47]
	ds_read_b128 v[64:67], v235 offset:8704
	v_exp_f32_e32 v92, v92
	v_exp_f32_e32 v93, v93
	v_add_f32_e32 v238, v238, v92
	v_add_f32_e32 v238, v238, v93
	v_fmamk_f32 v84, v201, 0x42100000, v254
	v_fmamk_f32 v85, v201, 0x42140000, v254
	s_waitcnt lgkmcnt(4)
	v_mfma_f32_32x32x16_bf16 v[16:31], v[72:75], v[144:147], v[16:31]
	ds_read_b128 v[68:71], v235 offset:8736
	v_exp_f32_e32 v94, v94
	v_exp_f32_e32 v95, v95
	v_add_f32_e32 v238, v238, v94
	v_add_f32_e32 v238, v238, v95
	v_fmamk_f32 v86, v201, 0x42180000, v254
	v_fmamk_f32 v87, v201, 0x421c0000, v254
	s_waitcnt lgkmcnt(4)
	v_mfma_f32_32x32x16_bf16 v[16:31], v[76:79], v[148:151], v[16:31]
	ds_read_b128 v[72:75], v235 offset:8768
	v_cvt_pk_bf16_f32 v156, v88, v89
	v_cvt_pk_bf16_f32 v157, v90, v91
	v_cvt_pk_bf16_f32 v158, v92, v93
	v_cvt_pk_bf16_f32 v159, v94, v95
	s_waitcnt lgkmcnt(4)
	v_mfma_f32_32x32x16_bf16 v[0:15], v[160:163], v[144:147], v[0:15]
	ds_read_b128 v[76:79], v235 offset:8800
	v_fmamk_f32 v88, v201, 0x42400000, v254
	v_fmamk_f32 v89, v201, 0x42440000, v254
	v_fmamk_f32 v90, v201, 0x42480000, v254
	v_fmamk_f32 v91, v201, 0x424c0000, v254
	v_add_f32_e32 v238, v238, v233
	s_waitcnt lgkmcnt(4)
	v_mfma_f32_32x32x16_bf16 v[0:15], v[244:247], v[148:151], v[0:15]
	ds_read_b128 v[160:163], v234 offset:34880
	v_fmamk_f32 v92, v201, 0x42500000, v254
	v_fmamk_f32 v93, v201, 0x42540000, v254
	v_fmamk_f32 v94, v201, 0x42580000, v254
	v_fmamk_f32 v95, v201, 0x425c0000, v254
	s_cmp_lt_u32 s90, 2
	s_cbranch_scc1 .LfixA_skip_h0_do
	s_cmp_lt_i32 s90, s38
	s_cbranch_scc1 .LfixA_skip_h0

.LfixA_skip_h0:
	s_setprio 1
	s_waitcnt lgkmcnt(4)
	v_mfma_f32_32x32x16_bf16 v[80:95], v[64:67], v[112:115], v[80:95]
	ds_read_b128 v[244:247], v234 offset:34912
	v_exp_f32_e32 v96, v96
	v_exp_f32_e32 v97, v97
	v_add_f32_e32 v233, 0, v96
	v_add_f32_e32 v233, v233, v97
	s_waitcnt lgkmcnt(4)
	v_mfma_f32_32x32x16_bf16 v[80:95], v[68:71], v[116:119], v[80:95]
	ds_read_b128 v[64:67], v234 offset:39488
	v_exp_f32_e32 v98, v98
	v_exp_f32_e32 v99, v99
	v_add_f32_e32 v233, v233, v98
	v_add_f32_e32 v233, v233, v99
	s_waitcnt lgkmcnt(4)
	v_mfma_f32_32x32x16_bf16 v[80:95], v[72:75], v[120:123], v[80:95]
	ds_read_b128 v[68:71], v234 offset:39520
	v_exp_f32_e32 v100, v100
	v_exp_f32_e32 v101, v101
	v_add_f32_e32 v233, v233, v100
	v_add_f32_e32 v233, v233, v101
	s_waitcnt lgkmcnt(4)
	v_mfma_f32_32x32x16_bf16 v[80:95], v[76:79], v[124:127], v[80:95]
	ds_read_b128 v[72:75], v234 offset:44096
	v_exp_f32_e32 v102, v102
	v_exp_f32_e32 v103, v103
	v_add_f32_e32 v233, v233, v102
	v_add_f32_e32 v233, v233, v103
	s_waitcnt lgkmcnt(4)
	v_mfma_f32_32x32x16_bf16 v[48:63], v[160:163], v[152:155], v[48:63]
	ds_read_b128 v[76:79], v234 offset:44128
	v_cvt_pk_bf16_f32 v144, v96, v97
	v_cvt_pk_bf16_f32 v145, v98, v99
	v_cvt_pk_bf16_f32 v146, v100, v101
	v_cvt_pk_bf16_f32 v147, v102, v103
	v_add_f32_e32 v255, 0x43000000, v237
	v_fma_f32 v254, v236, v255, v253
	s_waitcnt lgkmcnt(4)
	v_mfma_f32_32x32x16_bf16 v[48:63], v[244:247], v[156:159], v[48:63]
	ds_read_b128 v[160:163], v234 offset:48704
	v_exp_f32_e32 v104, v104
	v_exp_f32_e32 v105, v105
	v_add_f32_e32 v233, v233, v104
	v_add_f32_e32 v233, v233, v105
	v_fmamk_f32 v96, v201, 0x00000000, v254
	v_fmamk_f32 v97, v201, 0x3f800000, v254
	s_setprio 0
	s_waitcnt lgkmcnt(4)
	v_mfma_f32_32x32x16_bf16 v[32:47], v[64:67], v[152:155], v[32:47]
	ds_read_b128 v[244:247], v234 offset:48736
	v_exp_f32_e32 v106, v106
	v_exp_f32_e32 v107, v107
	v_add_f32_e32 v233, v233, v106
	v_add_f32_e32 v233, v233, v107
	v_fmamk_f32 v98, v201, 0x40000000, v254
	v_fmamk_f32 v99, v201, 0x40400000, v254
	s_waitcnt lgkmcnt(4)
	v_mfma_f32_32x32x16_bf16 v[32:47], v[68:71], v[156:159], v[32:47]
	v_exp_f32_e32 v108, v108
	v_exp_f32_e32 v109, v109
	v_add_f32_e32 v233, v233, v108
	v_add_f32_e32 v233, v233, v109
	v_fmamk_f32 v100, v201, 0x40800000, v254
	v_fmamk_f32 v101, v201, 0x40a00000, v254
	s_waitcnt lgkmcnt(3)
	v_mfma_f32_32x32x16_bf16 v[16:31], v[72:75], v[152:155], v[16:31]
	v_exp_f32_e32 v110, v110
	v_exp_f32_e32 v111, v111
	v_add_f32_e32 v233, v233, v110
	v_add_f32_e32 v233, v233, v111
	v_fmamk_f32 v102, v201, 0x40c00000, v254
	v_fmamk_f32 v103, v201, 0x40e00000, v254
	s_waitcnt lgkmcnt(2)
	v_mfma_f32_32x32x16_bf16 v[16:31], v[76:79], v[156:159], v[16:31]
	v_cvt_pk_bf16_f32 v148, v104, v105
	v_cvt_pk_bf16_f32 v149, v106, v107
	v_cvt_pk_bf16_f32 v150, v108, v109
	v_cvt_pk_bf16_f32 v151, v110, v111
	s_waitcnt lgkmcnt(1)
	v_mfma_f32_32x32x16_bf16 v[0:15], v[160:163], v[152:155], v[0:15]
	v_fmamk_f32 v104, v201, 0x41800000, v254
	v_fmamk_f32 v105, v201, 0x41880000, v254
	v_fmamk_f32 v106, v201, 0x41900000, v254
	v_fmamk_f32 v107, v201, 0x41980000, v254
	v_add_f32_e32 v233, v233, v238
	s_waitcnt lgkmcnt(0)
	v_mfma_f32_32x32x16_bf16 v[0:15], v[244:247], v[156:159], v[0:15]
	v_fmamk_f32 v108, v201, 0x41a00000, v254
	v_fmamk_f32 v109, v201, 0x41a80000, v254
	v_fmamk_f32 v110, v201, 0x41b00000, v254
	v_fmamk_f32 v111, v201, 0x41b80000, v254
	s_cmp_lt_u32 s90, 1
	s_cbranch_scc1 .LfixB_skip_h0_do
	s_cmp_lt_i32 s87, s38
	s_cbranch_scc1 .LfixB_skip_h0

.Lan_331_h1:
	v_cvt_f32_i32_e32 v237, v231
	s_setprio 0
	s_waitcnt lgkmcnt(4)
	v_mfma_f32_32x32x16_bf16 v[96:111], v[64:67], v[112:115], v[96:111]
	ds_read_b128 v[244:247], v234 offset:34848
	v_exp_f32_e32 v80, v80
	v_exp_f32_e32 v81, v81
	v_add_f32_e32 v238, 0, v80
	v_add_f32_e32 v238, v238, v81
	s_waitcnt lgkmcnt(4)
	v_mfma_f32_32x32x16_bf16 v[96:111], v[68:71], v[116:119], v[96:111]
	ds_read_b128 v[64:67], v234 offset:39424
	v_exp_f32_e32 v82, v82
	v_exp_f32_e32 v83, v83
	v_add_f32_e32 v238, v238, v82
	v_add_f32_e32 v238, v238, v83
	s_waitcnt lgkmcnt(4)
	v_mfma_f32_32x32x16_bf16 v[96:111], v[72:75], v[120:123], v[96:111]
	ds_read_b128 v[68:71], v234 offset:39456
	v_exp_f32_e32 v84, v84
	v_exp_f32_e32 v85, v85
	v_add_f32_e32 v238, v238, v84
	v_add_f32_e32 v238, v238, v85
	s_waitcnt lgkmcnt(4)
	v_mfma_f32_32x32x16_bf16 v[96:111], v[76:79], v[124:127], v[96:111]
	ds_read_b128 v[72:75], v234 offset:44032
	v_exp_f32_e32 v86, v86
	v_exp_f32_e32 v87, v87
	v_add_f32_e32 v238, v238, v86
	v_add_f32_e32 v238, v238, v87
	s_waitcnt lgkmcnt(4)
	v_mfma_f32_32x32x16_bf16 v[48:63], v[160:163], v[144:147], v[48:63]
	ds_read_b128 v[76:79], v234 offset:44064
	v_cvt_pk_bf16_f32 v152, v80, v81
	v_cvt_pk_bf16_f32 v153, v82, v83
	v_cvt_pk_bf16_f32 v154, v84, v85
	v_cvt_pk_bf16_f32 v155, v86, v87
	v_add_f32_e32 v255, 0x42800000, v237
	v_fma_f32 v254, v236, v255, v253
	s_waitcnt lgkmcnt(4)
	v_mfma_f32_32x32x16_bf16 v[48:63], v[244:247], v[148:151], v[48:63]
	ds_read_b128 v[160:163], v234 offset:48640
	v_exp_f32_e32 v88, v88
	v_exp_f32_e32 v89, v89
	v_add_f32_e32 v238, v238, v88
	v_add_f32_e32 v238, v238, v89
	v_fmamk_f32 v80, v201, 0x42000000, v254
	v_fmamk_f32 v81, v201, 0x42040000, v254
	s_setprio 1
	s_waitcnt lgkmcnt(4)
	v_mfma_f32_32x32x16_bf16 v[32:47], v[64:67], v[144:147], v[32:47]
	ds_read_b128 v[244:247], v234 offset:48672
	v_exp_f32_e32 v90, v90
	v_exp_f32_e32 v91, v91
	v_add_f32_e32 v238, v238, v90
	v_add_f32_e32 v238, v238, v91
	v_fmamk_f32 v82, v201, 0x42080000, v254
	v_fmamk_f32 v83, v201, 0x420c0000, v254
	s_waitcnt lgkmcnt(4)
	v_mfma_f32_32x32x16_bf16 v[32:47], v[68:71], v[148:151], v[32:47]
	ds_read_b128 v[64:67], v235 offset:8704
	v_exp_f32_e32 v92, v92
	v_exp_f32_e32 v93, v93
	v_add_f32_e32 v238, v238, v92
	v_add_f32_e32 v238, v238, v93
	v_fmamk_f32 v84, v201, 0x42100000, v254
	v_fmamk_f32 v85, v201, 0x42140000, v254
	s_waitcnt lgkmcnt(4)
	v_mfma_f32_32x32x16_bf16 v[16:31], v[72:75], v[144:147], v[16:31]
	ds_read_b128 v[68:71], v235 offset:8736
	v_exp_f32_e32 v94, v94
	v_exp_f32_e32 v95, v95
	v_add_f32_e32 v238, v238, v94
	v_add_f32_e32 v238, v238, v95
	v_fmamk_f32 v86, v201, 0x42180000, v254
	v_fmamk_f32 v87, v201, 0x421c0000, v254
	s_waitcnt lgkmcnt(4)
	v_mfma_f32_32x32x16_bf16 v[16:31], v[76:79], v[148:151], v[16:31]
	ds_read_b128 v[72:75], v235 offset:8768
	v_cvt_pk_bf16_f32 v156, v88, v89
	v_cvt_pk_bf16_f32 v157, v90, v91
	v_cvt_pk_bf16_f32 v158, v92, v93
	v_cvt_pk_bf16_f32 v159, v94, v95
	s_waitcnt lgkmcnt(4)
	v_mfma_f32_32x32x16_bf16 v[0:15], v[160:163], v[144:147], v[0:15]
	ds_read_b128 v[76:79], v235 offset:8800
	v_fmamk_f32 v88, v201, 0x42400000, v254
	v_fmamk_f32 v89, v201, 0x42440000, v254
	v_fmamk_f32 v90, v201, 0x42480000, v254
	v_fmamk_f32 v91, v201, 0x424c0000, v254
	v_add_f32_e32 v238, v238, v233
	s_waitcnt lgkmcnt(4)
	v_mfma_f32_32x32x16_bf16 v[0:15], v[244:247], v[148:151], v[0:15]
	ds_read_b128 v[160:163], v234 offset:34880
	v_fmamk_f32 v92, v201, 0x42500000, v254
	v_fmamk_f32 v93, v201, 0x42540000, v254
	v_fmamk_f32 v94, v201, 0x42580000, v254
	v_fmamk_f32 v95, v201, 0x425c0000, v254
	s_cmp_lt_u32 s90, 2
	s_cbranch_scc1 .LfixA_skip_h1_do
	s_cmp_lt_i32 s90, s38
	s_cbranch_scc1 .LfixA_skip_h1

.LfixA_skip_h1:
	s_setprio 0
	s_waitcnt lgkmcnt(4)
	v_mfma_f32_32x32x16_bf16 v[80:95], v[64:67], v[112:115], v[80:95]
	ds_read_b128 v[244:247], v234 offset:34912
	v_exp_f32_e32 v96, v96
	v_exp_f32_e32 v97, v97
	v_add_f32_e32 v233, 0, v96
	v_add_f32_e32 v233, v233, v97
	s_waitcnt lgkmcnt(4)
	v_mfma_f32_32x32x16_bf16 v[80:95], v[68:71], v[116:119], v[80:95]
	ds_read_b128 v[64:67], v234 offset:39488
	v_exp_f32_e32 v98, v98
	v_exp_f32_e32 v99, v99
	v_add_f32_e32 v233, v233, v98
	v_add_f32_e32 v233, v233, v99
	s_waitcnt lgkmcnt(4)
	v_mfma_f32_32x32x16_bf16 v[80:95], v[72:75], v[120:123], v[80:95]
	ds_read_b128 v[68:71], v234 offset:39520
	v_exp_f32_e32 v100, v100
	v_exp_f32_e32 v101, v101
	v_add_f32_e32 v233, v233, v100
	v_add_f32_e32 v233, v233, v101
	s_waitcnt lgkmcnt(4)
	v_mfma_f32_32x32x16_bf16 v[80:95], v[76:79], v[124:127], v[80:95]
	ds_read_b128 v[72:75], v234 offset:44096
	v_exp_f32_e32 v102, v102
	v_exp_f32_e32 v103, v103
	v_add_f32_e32 v233, v233, v102
	v_add_f32_e32 v233, v233, v103
	s_waitcnt lgkmcnt(4)
	v_mfma_f32_32x32x16_bf16 v[48:63], v[160:163], v[152:155], v[48:63]
	ds_read_b128 v[76:79], v234 offset:44128
	v_cvt_pk_bf16_f32 v144, v96, v97
	v_cvt_pk_bf16_f32 v145, v98, v99
	v_cvt_pk_bf16_f32 v146, v100, v101
	v_cvt_pk_bf16_f32 v147, v102, v103
	v_add_f32_e32 v255, 0x43000000, v237
	v_fma_f32 v254, v236, v255, v253
	s_waitcnt lgkmcnt(4)
	v_mfma_f32_32x32x16_bf16 v[48:63], v[244:247], v[156:159], v[48:63]
	ds_read_b128 v[160:163], v234 offset:48704
	v_exp_f32_e32 v104, v104
	v_exp_f32_e32 v105, v105
	v_add_f32_e32 v233, v233, v104
	v_add_f32_e32 v233, v233, v105
	v_fmamk_f32 v96, v201, 0x00000000, v254
	v_fmamk_f32 v97, v201, 0x3f800000, v254
	s_setprio 1
	s_waitcnt lgkmcnt(4)
	v_mfma_f32_32x32x16_bf16 v[32:47], v[64:67], v[152:155], v[32:47]
	ds_read_b128 v[244:247], v234 offset:48736
	v_exp_f32_e32 v106, v106
	v_exp_f32_e32 v107, v107
	v_add_f32_e32 v233, v233, v106
	v_add_f32_e32 v233, v233, v107
	v_fmamk_f32 v98, v201, 0x40000000, v254
	v_fmamk_f32 v99, v201, 0x40400000, v254
	s_waitcnt lgkmcnt(4)
	v_mfma_f32_32x32x16_bf16 v[32:47], v[68:71], v[156:159], v[32:47]
	v_exp_f32_e32 v108, v108
	v_exp_f32_e32 v109, v109
	v_add_f32_e32 v233, v233, v108
	v_add_f32_e32 v233, v233, v109
	v_fmamk_f32 v100, v201, 0x40800000, v254
	v_fmamk_f32 v101, v201, 0x40a00000, v254
	s_waitcnt lgkmcnt(3)
	v_mfma_f32_32x32x16_bf16 v[16:31], v[72:75], v[152:155], v[16:31]
	v_exp_f32_e32 v110, v110
	v_exp_f32_e32 v111, v111
	v_add_f32_e32 v233, v233, v110
	v_add_f32_e32 v233, v233, v111
	v_fmamk_f32 v102, v201, 0x40c00000, v254
	v_fmamk_f32 v103, v201, 0x40e00000, v254
	s_waitcnt lgkmcnt(2)
	v_mfma_f32_32x32x16_bf16 v[16:31], v[76:79], v[156:159], v[16:31]
	v_cvt_pk_bf16_f32 v148, v104, v105
	v_cvt_pk_bf16_f32 v149, v106, v107
	v_cvt_pk_bf16_f32 v150, v108, v109
	v_cvt_pk_bf16_f32 v151, v110, v111
	s_waitcnt lgkmcnt(1)
	v_mfma_f32_32x32x16_bf16 v[0:15], v[160:163], v[152:155], v[0:15]
	v_fmamk_f32 v104, v201, 0x41800000, v254
	v_fmamk_f32 v105, v201, 0x41880000, v254
	v_fmamk_f32 v106, v201, 0x41900000, v254
	v_fmamk_f32 v107, v201, 0x41980000, v254
	v_add_f32_e32 v233, v233, v238
	s_waitcnt lgkmcnt(0)
	v_mfma_f32_32x32x16_bf16 v[0:15], v[244:247], v[156:159], v[0:15]
	v_fmamk_f32 v108, v201, 0x41a00000, v254
	v_fmamk_f32 v109, v201, 0x41a80000, v254
	v_fmamk_f32 v110, v201, 0x41b00000, v254
	v_fmamk_f32 v111, v201, 0x41b80000, v254
	s_cmp_lt_u32 s90, 1
	s_cbranch_scc1 .LfixB_skip_h1_do
	s_cmp_lt_i32 s87, s38
	s_cbranch_scc1 .LfixB_skip_h1
